# x_in (input cast) loop: all 8 row loads issued together with one wait instead of 8 serialized load-wait pairs
# baseline (speedup 1.0000x reference)
; __device__ __forceinline__ unsigned cvt_pk_bf16(float lo, float hi) { unsigned r; asm volatile("v_cvt_pk_bf16_f32 %0, %1, %2" : "=v"(r) : "v"(lo), "v"(hi)); return r; }
; __device__ __forceinline__ void x_in_phase(const Ctx& C, const float* src, bf16_t* xn, float* hss) {
;     ...
;     for (int m = gw; m < M_TOK; m += NGW) {
;         const f32x4* xr = (const f32x4*)(src + (size_t)m * DM) + C.lane;
;         f32x4 v[8]; float ss = 0.f;
; #pragma unroll
;         for (int j = 0; j < 8; ++j) { v[j] = xr[64 * j]; ss += (v[j][0] * v[j][0] + v[j][1] * v[j][1]) + (v[j][2] * v[j][2] + v[j][3] * v[j][3]); }
;         ss = wave_sum(ss);
;         u32x2* o = (u32x2*)(xn + (size_t)m * DM) + C.lane;
; #pragma unroll
;         for (int j = 0; j < 8; ++j) { u32x2 w; w.x = cvt_pk_bf16(v[j][0], v[j][1]); w.y = cvt_pk_bf16(v[j][2], v[j][3]); o[64 * j] = w; }
;         if (C.lane < 32) hss[(size_t)m * 64 + C.lane] = C.lane == 0 ? ss : 0.f;
;     }
.LBB0_567:
	s_movk_i32 s0, 0x1000
	v_add_co_u32_e64 v24, s[0:1], s0, v36
	global_load_dwordx4 v[28:31], v[36:37], off
	global_load_dwordx4 v[0:3], v[36:37], off offset:1024
	v_addc_co_u32_e64 v25, s[0:1], 0, v37, s[0:1]
	global_load_dwordx4 v[4:7], v[36:37], off offset:2048
	global_load_dwordx4 v[8:11], v[36:37], off offset:3072
	s_mov_b32 s0, 0x18800000
	global_load_dwordx4 v[12:15], v[24:25], off
	global_load_dwordx4 v[16:19], v[24:25], off offset:1024
	global_load_dwordx4 v[20:23], v[24:25], off offset:2048
	global_load_dwordx4 v[24:27], v[24:25], off offset:3072
	s_waitcnt vmcnt(0)
	v_mul_f32_e32 v48, v29, v29
	v_mul_f32_e32 v49, v31, v31
	v_fmac_f32_e32 v48, v28, v28
	v_fmac_f32_e32 v49, v30, v30
	v_add_f32_e32 v44, v48, v49
	v_mul_f32_e32 v48, v1, v1
	v_mul_f32_e32 v49, v3, v3
	v_fmac_f32_e32 v48, v0, v0
	v_fmac_f32_e32 v49, v2, v2
	v_add_f32_e32 v48, v48, v49
	v_add_f32_e32 v44, v44, v48
	v_mul_f32_e32 v48, v5, v5
	v_mul_f32_e32 v49, v7, v7
	v_fmac_f32_e32 v48, v4, v4
	v_fmac_f32_e32 v49, v6, v6
	v_add_f32_e32 v48, v48, v49
	v_add_f32_e32 v44, v44, v48
	v_mul_f32_e32 v48, v9, v9
	v_mul_f32_e32 v49, v11, v11
	v_fmac_f32_e32 v48, v8, v8
	v_fmac_f32_e32 v49, v10, v10
	v_add_f32_e32 v48, v48, v49
	v_add_f32_e32 v44, v44, v48
	v_mul_f32_e32 v48, v13, v13
	v_mul_f32_e32 v49, v15, v15
	v_fmac_f32_e32 v48, v12, v12
	v_fmac_f32_e32 v49, v14, v14
	v_add_f32_e32 v48, v48, v49
	v_add_f32_e32 v44, v44, v48
	v_mul_f32_e32 v48, v17, v17
	v_mul_f32_e32 v49, v19, v19
	v_fmac_f32_e32 v48, v16, v16
	v_fmac_f32_e32 v49, v18, v18
	v_add_f32_e32 v48, v48, v49
	v_add_f32_e32 v44, v44, v48
	v_mul_f32_e32 v48, v21, v21
	v_mul_f32_e32 v49, v23, v23
	v_fmac_f32_e32 v48, v20, v20
	v_fmac_f32_e32 v49, v22, v22
	v_add_f32_e32 v48, v48, v49
	v_add_f32_e32 v44, v44, v48
	v_mul_f32_e32 v48, v25, v25
	v_mul_f32_e32 v49, v27, v27
	v_fmac_f32_e32 v48, v24, v24
	v_fmac_f32_e32 v49, v26, v26
	v_add_f32_e32 v48, v48, v49
	v_add_f32_e32 v44, v44, v48
	v_cvt_pk_bf16_f32 v28, v28, v29
	v_cvt_pk_bf16_f32 v29, v30, v31
	ds_bpermute_b32 v45, v38, v44
	v_lshl_add_u64 v[46:47], s[66:67], 0, v[34:35]
	v_add_co_u32_e64 v30, s[0:1], s0, v46
	s_waitcnt lgkmcnt(0)
	v_add_f32_e32 v44, v44, v45
	ds_bpermute_b32 v45, v39, v44
	v_addc_co_u32_e64 v31, s[0:1], 0, v47, s[0:1]
	global_store_dwordx2 v[30:31], v[28:29], off
	v_cvt_pk_bf16_f32 v0, v0, v1
	s_waitcnt lgkmcnt(0)
	v_add_f32_e32 v44, v44, v45
	ds_bpermute_b32 v45, v40, v44
	v_cvt_pk_bf16_f32 v1, v2, v3
	global_store_dwordx2 v[30:31], v[0:1], off offset:512
	v_cvt_pk_bf16_f32 v0, v4, v5
	v_cvt_pk_bf16_f32 v1, v6, v7
	s_waitcnt lgkmcnt(0)
	v_add_f32_e32 v44, v44, v45
	ds_bpermute_b32 v45, v41, v44
	global_store_dwordx2 v[30:31], v[0:1], off offset:1024
	v_cvt_pk_bf16_f32 v0, v8, v9
	v_cvt_pk_bf16_f32 v1, v10, v11
	global_store_dwordx2 v[30:31], v[0:1], off offset:1536
	s_waitcnt lgkmcnt(0)
	v_add_f32_e32 v44, v44, v45
	ds_bpermute_b32 v45, v42, v44
	v_cvt_pk_bf16_f32 v0, v12, v13
	v_cvt_pk_bf16_f32 v1, v14, v15
	global_store_dwordx2 v[30:31], v[0:1], off offset:2048
	v_cvt_pk_bf16_f32 v0, v16, v17
	s_waitcnt lgkmcnt(0)
	v_add_f32_e32 v44, v44, v45
	ds_bpermute_b32 v45, v43, v44
	v_cvt_pk_bf16_f32 v1, v18, v19
	global_store_dwordx2 v[30:31], v[0:1], off offset:2560
	v_cvt_pk_bf16_f32 v0, v20, v21
	v_cvt_pk_bf16_f32 v1, v22, v23
	global_store_dwordx2 v[30:31], v[0:1], off offset:3072
	v_cvt_pk_bf16_f32 v0, v24, v25
	v_cvt_pk_bf16_f32 v1, v26, v27
	global_store_dwordx2 v[30:31], v[0:1], off offset:3584
	s_and_saveexec_b64 s[0:1], vcc
	s_cbranch_execz .LBB0_566
	s_waitcnt lgkmcnt(0)
	v_add_f32_e32 v0, v44, v45
	v_cndmask_b32_e64 v2, 0, v0, s[38:39]
	v_lshl_add_u64 v[0:1], s[66:67], 0, v[32:33]
	global_store_dword v[0:1], v2, off
	s_branch .LBB0_566
